# GDN mini-chunk: rhs precomputed in accumulator layout, d-chain-only forward substitution, outputs o=ec*QS0+A2*D via f32 MFMA (v_mfma_f32_16x16x4_f32) instead of per-step VALU/DPP
# speedup vs baseline: 1.0301x; 1.0114x over previous
; __device__ __forceinline__ void gdn_block4(const Params& p, int l, int b, int h, int dir, char* smem, bool ctx_out) {
;     ...
;         f32x4 ks0 = f32x4{0.f, 0.f, 0.f, 0.f}, qs0 = f32x4{0.f, 0.f, 0.f, 0.f};
; #pragma unroll
;         for (int ks = 0; ks < 2; ++ks) {
;           const float* kr = Lk + (tb + fr) * 68;
;           const float* qr = Lq + (tb + fr) * 68;
;           const float4 c0 = *reinterpret_cast<const float4*>(kr + (2 * ks) * 16 + fq * 4), c1 = *reinterpret_cast<const float4*>(kr + (2 * ks + 1) * 16 + fq * 4);
;           const float4 d0 = *reinterpret_cast<const float4*>(qr + (2 * ks) * 16 + fq * 4), d1 = *reinterpret_cast<const float4*>(qr + (2 * ks + 1) * 16 + fq * 4);
;           const uint4 uc = make_uint4(pack2(c0.x, c0.y), pack2(c0.z, c0.w), pack2(c1.x, c1.y), pack2(c1.z, c1.w));
;           const uint4 ud = make_uint4(pack2(d0.x, d0.y), pack2(d0.z, d0.w), pack2(d1.x, d1.y), pack2(d1.z, d1.w));
;           const uint4 us = make_uint4(pack2(Sacc[2 * ks][0], Sacc[2 * ks][1]), pack2(Sacc[2 * ks][2], Sacc[2 * ks][3]),
;                                       pack2(Sacc[2 * ks + 1][0], Sacc[2 * ks + 1][1]), pack2(Sacc[2 * ks + 1][2], Sacc[2 * ks + 1][3]));
;           const bf16x8 sf = __builtin_bit_cast(bf16x8, us);
;           ks0 = __builtin_amdgcn_mfma_f32_16x16x32_bf16(__builtin_bit_cast(bf16x8, uc), sf, ks0, 0, 0, 0);
;           qs0 = __builtin_amdgcn_mfma_f32_16x16x32_bf16(__builtin_bit_cast(bf16x8, ud), sf, qs0, 0, 0, 0);
;         }
; #pragma unroll
;         for (int i = 0; i < 4; ++i) { KSs[(fq * 4 + i) * 16 + fr] = ks0[i]; QSs[(fq * 4 + i) * 16 + fr] = qs0[i]; }
;         WAVE_SYNC();
;         float dreg[4] = {0.f, 0.f, 0.f, 0.f};
;         float na1[4], na2[4], nbt, nec, nv, nks, nqs;
; #pragma unroll
;         for (int j = 0; j < 4; ++j) { na1[j] = A1[sq + 4 * j]; na2[j] = A2[sq + 4 * j]; }
;         nbt = Bts[0]; nec = Ecs[0]; nv = Lv[tb * 68 + wid * 16 + vq]; nks = KSs[vq]; nqs = QSs[vq];
; #pragma unroll
;         for (int t = 0; t < 16; ++t) {
;           float a1[4], a2[4];
; #pragma unroll
;           for (int j = 0; j < 4; ++j) { a1[j] = na1[j]; a2[j] = na2[j]; }
;           const float bt = nbt, ec = nec, vv = nv, ksv = nks, qsv = nqs;
;           if (t < 15) {
; #pragma unroll
;             for (int j = 0; j < (t + 4) / 4; ++j) na1[j] = A1[(t + 1) * 16 + sq + 4 * j];
; #pragma unroll
.LBB0_1242:
	s_lshl_b32 vcc_lo, s90, 4
	v_or_b32_e32 v2, vcc_lo, v97
	v_mul_u32_u24_e32 v2, 0x44, v2
	v_lshl_add_u32 v2, v2, 2, v125
	ds_read_b128 v[56:59], v2
	ds_read_b128 v[60:63], v2 offset:64
	ds_read_b128 v[64:67], v2 offset:8704
	ds_read_b128 v[68:71], v2 offset:8768
	s_mul_i32 s91, s90, 0xa00
	s_waitcnt lgkmcnt(3)
	v_cvt_pk_bf16_f32 v56, v56, v57
	v_cvt_pk_bf16_f32 v57, v58, v59
	s_waitcnt lgkmcnt(2)
	v_cvt_pk_bf16_f32 v58, v60, v61
	v_cvt_pk_bf16_f32 v59, v62, v63
	s_waitcnt lgkmcnt(1)
	v_cvt_pk_bf16_f32 v60, v64, v65
	v_cvt_pk_bf16_f32 v61, v66, v67
	s_waitcnt lgkmcnt(0)
	v_cvt_pk_bf16_f32 v62, v68, v69
	v_cvt_pk_bf16_f32 v63, v70, v71
	v_cvt_pk_bf16_f32 v64, v52, v53
	v_cvt_pk_bf16_f32 v65, v54, v55
	v_cvt_pk_bf16_f32 v66, v48, v49
	v_cvt_pk_bf16_f32 v67, v50, v51
	ds_read_b128 v[68:71], v2 offset:128
	s_add_i32 vcc_hi, s33, s91
	v_mfma_f32_16x16x32_bf16 v[56:59], v[56:59], v[64:67], 0
	v_lshl_add_u32 v73, v106, 2, vcc_hi
	s_mul_i32 s91, s90, 0x1100
	s_waitcnt lgkmcnt(0)
	v_cvt_pk_bf16_f32 v68, v68, v69
	v_mfma_f32_16x16x32_bf16 v[60:63], v[60:63], v[64:67], 0
	ds_read_b128 v[64:67], v2 offset:192
	ds_read_b128 v[132:135], v2 offset:8832
	ds_read_b128 v[136:139], v2 offset:8896
	v_cvt_pk_bf16_f32 v69, v70, v71
	v_add_u32_e32 v2, 0x400, v119
	s_waitcnt lgkmcnt(2)
	v_cvt_pk_bf16_f32 v70, v64, v65
	v_cvt_pk_bf16_f32 v71, v66, v67
	s_waitcnt lgkmcnt(1)
	v_cvt_pk_bf16_f32 v64, v132, v133
	v_cvt_pk_bf16_f32 v65, v134, v135
	s_waitcnt lgkmcnt(0)
	v_cvt_pk_bf16_f32 v66, v136, v137
	v_cvt_pk_bf16_f32 v67, v138, v139
	v_cvt_pk_bf16_f32 v132, v44, v45
	v_cvt_pk_bf16_f32 v133, v46, v47
	v_cvt_pk_bf16_f32 v134, v40, v41
	v_cvt_pk_bf16_f32 v135, v42, v43
	v_add_u32_e32 v86, 0x400, v73
	s_add_i32 s96, s79, s91
	v_mfma_f32_16x16x32_bf16 v[56:59], v[68:71], v[132:135], v[56:59]
	v_mov_b32_e32 v72, vcc_hi
	v_lshl_add_u32 v87, v107, 2, s96
	v_lshl_add_u32 v128, s90, 12, v127
	v_mfma_f32_16x16x32_bf16 v[60:63], v[64:67], v[132:135], v[60:63]
	v_lshlrev_b32_e32 v2, 2, v98
	v_add_u32_e32 v2, vcc_hi, v2
	ds_read_b128 v[64:67], v2 offset:2176
	ds_read_b128 v[68:71], v2 offset:2048
	v_lshl_or_b32 v3, v88, 4, v97
	v_mul_u32_u24_e32 v129, 0x110, v98
	v_lshl_add_u32 v129, v3, 2, v129
	v_add_u32_e32 v129, s96, v129
	ds_read_b32 v132, v129 offset:17408
	ds_read_b32 v133, v129 offset:17680
	ds_read_b32 v134, v129 offset:17952
	ds_read_b32 v135, v129 offset:18224
	v_and_b32_e32 v131, 60, v102
	v_sub_u32_e32 v131, v128, v131
	v_lshl_add_u32 v131, v97, 2, v131
	v_lshl_add_u32 v131, v98, 8, v131
	s_waitcnt lgkmcnt(0)
	v_mul_f32_e32 v136, v64, v68
	v_mul_f32_e32 v137, v65, v69
	v_mul_f32_e32 v138, v66, v70
	v_mul_f32_e32 v139, v67, v71
	v_mul_f32_e32 v132, v64, v132
	v_mul_f32_e32 v133, v65, v133
	v_mul_f32_e32 v134, v66, v134
	v_mul_f32_e32 v135, v67, v135
	v_fma_f32 v132, -v136, v56, v132
	v_fma_f32 v133, -v137, v57, v133
	v_fma_f32 v134, -v138, v58, v134
	v_fma_f32 v135, -v139, v59, v135
	v_mul_f32_e32 v60, v68, v60
	v_mul_f32_e32 v61, v69, v61
	v_mul_f32_e32 v62, v70, v62
	v_mul_f32_e32 v63, v71, v63
	ds_write2_b32 v119, v132, v133 offset1:16
	ds_write2_b32 v119, v134, v135 offset0:32 offset1:48
	ds_read2_b32 v[132:133], v73 offset0:0 offset1:4
	ds_read2_b32 v[134:135], v73 offset0:8 offset1:12
	ds_read_b32 v136, v108 offset:0
	ds_read2_b32 v[138:139], v73 offset0:16 offset1:20
	ds_read2_b32 v[140:141], v73 offset0:24 offset1:28
	ds_read_b32 v137, v108 offset:64
	ds_read2_b32 v[68:69], v73 offset0:32 offset1:36
	ds_read2_b32 v[70:71], v73 offset0:40 offset1:44
	ds_read_b32 v142, v108 offset:128
	v_mov_b32_e32 v64, 0
	v_mov_b32_e32 v65, 0
	v_mov_b32_e32 v66, 0
	v_mov_b32_e32 v67, 0
	s_waitcnt lgkmcnt(6)
	v_mul_f32_e32 v2, v133, v65
	v_fmac_f32_e32 v2, v134, v66
	v_fmac_f32_e32 v2, v135, v67
	v_fmac_f32_e32 v2, v132, v64
	ds_read2_b32 v[132:133], v73 offset0:48 offset1:52
	ds_read2_b32 v[134:135], v73 offset0:56 offset1:60
	v_add_f32_dpp v2, v2, v2 quad_perm:[1,0,3,2] row_mask:0xf bank_mask:0xf bound_ctrl:1
	s_nop 1
	v_add_f32_dpp v2, v2, v2 quad_perm:[2,3,0,1] row_mask:0xf bank_mask:0xf bound_ctrl:1
	v_sub_f32_e32 v3, v136, v2
	ds_read_b32 v136, v108 offset:192
	v_cndmask_b32_e64 v64, v64, v3, s[62:63]
	ds_write_b32 v123, v3 offset:2048
	s_waitcnt lgkmcnt(7)
	v_mul_f32_e32 v2, v139, v65
	v_fmac_f32_e32 v2, v140, v66
	v_fmac_f32_e32 v2, v141, v67
	v_fmac_f32_e32 v2, v138, v64
	ds_read2_b32 v[138:139], v73 offset0:64 offset1:68
	ds_read2_b32 v[140:141], v73 offset0:72 offset1:76
	v_add_f32_dpp v2, v2, v2 quad_perm:[1,0,3,2] row_mask:0xf bank_mask:0xf bound_ctrl:1
	s_nop 1
	v_add_f32_dpp v2, v2, v2 quad_perm:[2,3,0,1] row_mask:0xf bank_mask:0xf bound_ctrl:1
	v_sub_f32_e32 v129, v137, v2
	ds_read_b32 v137, v108 offset:256
	v_cndmask_b32_e64 v64, v64, v129, s[64:65]
	ds_write_b32 v123, v129 offset:2052
	s_waitcnt lgkmcnt(8)
	v_mul_f32_e32 v2, v69, v65
	v_fmac_f32_e32 v2, v70, v66
	v_fmac_f32_e32 v2, v71, v67
	v_fmac_f32_e32 v2, v68, v64
	ds_read2_b32 v[68:69], v73 offset0:80 offset1:84
	ds_read2_b32 v[70:71], v73 offset0:88 offset1:92
	v_add_f32_dpp v2, v2, v2 quad_perm:[1,0,3,2] row_mask:0xf bank_mask:0xf bound_ctrl:1
	s_nop 1
	v_add_f32_dpp v2, v2, v2 quad_perm:[2,3,0,1] row_mask:0xf bank_mask:0xf bound_ctrl:1
	v_sub_f32_e32 v3, v142, v2
	ds_read_b32 v142, v108 offset:320
	v_cndmask_b32_e64 v64, v64, v3, s[66:67]
	ds_write_b32 v123, v3 offset:2056
	s_waitcnt lgkmcnt(9)
	v_mul_f32_e32 v2, v133, v65
	v_fmac_f32_e32 v2, v134, v66
	v_fmac_f32_e32 v2, v135, v67
	v_fmac_f32_e32 v2, v132, v64
	ds_read2_b32 v[132:133], v73 offset0:96 offset1:100
	ds_read2_b32 v[134:135], v73 offset0:104 offset1:108
	v_add_f32_dpp v2, v2, v2 quad_perm:[1,0,3,2] row_mask:0xf bank_mask:0xf bound_ctrl:1
	s_nop 1
	v_add_f32_dpp v2, v2, v2 quad_perm:[2,3,0,1] row_mask:0xf bank_mask:0xf bound_ctrl:1
	v_sub_f32_e32 v129, v136, v2
	ds_read_b32 v136, v108 offset:384
	v_cndmask_b32_e64 v64, v64, v129, s[68:69]
	ds_write_b32 v123, v129 offset:2060
	s_waitcnt lgkmcnt(9)
; __device__ __forceinline__ void gdn_block4(const Params& p, int l, int b, int h, int dir, char* smem, bool ctx_out) {
;     ...
; #pragma unroll
;         for (int t = 0; t < 16; ++t) {
;           float a1[4], a2[4];
; #pragma unroll
;           for (int j = 0; j < 4; ++j) { a1[j] = na1[j]; a2[j] = na2[j]; }
;           const float bt = nbt, ec = nec, vv = nv, ksv = nks, qsv = nqs;
;           if (t < 15) {
; #pragma unroll
;             for (int j = 0; j < (t + 4) / 4; ++j) na1[j] = A1[(t + 1) * 16 + sq + 4 * j];
; #pragma unroll
;             for (int j = 0; j <= ((t + 1) >> 2); ++j) na2[j] = A2[(t + 1) * 16 + sq + 4 * j];
;             nbt = Bts[t + 1]; nec = Ecs[t + 1]; nv = Lv[(tb + t + 1) * 68 + wid * 16 + vq]; nks = KSs[(t + 1) * 16 + vq]; nqs = QSs[(t + 1) * 16 + vq];
;           }
;           float part = 0.f;
; #pragma unroll
;           for (int j = 0; j < (t + 3) / 4; ++j) part += a1[j] * dreg[j];
;           part = reduce4(part);
;           const float dt = bt * vv - bt * ec * ksv - part;
;           dreg[t >> 2] = (sq == (t & 3)) ? dt : dreg[t >> 2];
;           float po = 0.f;
; #pragma unroll
;           for (int j = 0; j <= (t >> 2); ++j) po += a2[j] * dreg[j];
;           po = reduce4(po);
;           Lo[(tb + t) * 64 + wid * 16 + vq] = ec * qsv + po;
;           DlT[vq * 16 + t] = dt;
;         }
	v_mul_f32_e32 v2, v139, v65
	v_fmac_f32_e32 v2, v140, v66
	v_fmac_f32_e32 v2, v141, v67
	v_fmac_f32_e32 v2, v138, v64
	ds_read2_b32 v[138:139], v73 offset0:112 offset1:116
	ds_read2_b32 v[140:141], v73 offset0:120 offset1:124
	v_add_f32_dpp v2, v2, v2 quad_perm:[1,0,3,2] row_mask:0xf bank_mask:0xf bound_ctrl:1
	s_nop 1
	v_add_f32_dpp v2, v2, v2 quad_perm:[2,3,0,1] row_mask:0xf bank_mask:0xf bound_ctrl:1
	v_sub_f32_e32 v3, v137, v2
	ds_read_b32 v137, v108 offset:448
	v_cndmask_b32_e64 v65, v65, v3, s[62:63]
	ds_write_b32 v123, v3 offset:2064
	s_waitcnt lgkmcnt(9)
	v_mul_f32_e32 v2, v68, v64
	v_fmac_f32_e32 v2, v70, v66
	v_fmac_f32_e32 v2, v71, v67
	v_fmac_f32_e32 v2, v69, v65
	ds_read2_b32 v[68:69], v73 offset0:128 offset1:132
	ds_read2_b32 v[70:71], v73 offset0:136 offset1:140
	v_add_f32_dpp v2, v2, v2 quad_perm:[1,0,3,2] row_mask:0xf bank_mask:0xf bound_ctrl:1
	s_nop 1
	v_add_f32_dpp v2, v2, v2 quad_perm:[2,3,0,1] row_mask:0xf bank_mask:0xf bound_ctrl:1
	v_sub_f32_e32 v129, v142, v2
	ds_read_b32 v142, v108 offset:512
	v_cndmask_b32_e64 v65, v65, v129, s[64:65]
	ds_write_b32 v123, v129 offset:2068
	s_waitcnt lgkmcnt(9)
	v_mul_f32_e32 v2, v132, v64
	v_fmac_f32_e32 v2, v134, v66
	v_fmac_f32_e32 v2, v135, v67
	v_fmac_f32_e32 v2, v133, v65
	ds_read2_b32 v[132:133], v73 offset0:144 offset1:148
	ds_read2_b32 v[134:135], v73 offset0:152 offset1:156
	v_add_f32_dpp v2, v2, v2 quad_perm:[1,0,3,2] row_mask:0xf bank_mask:0xf bound_ctrl:1
	s_nop 1
	v_add_f32_dpp v2, v2, v2 quad_perm:[2,3,0,1] row_mask:0xf bank_mask:0xf bound_ctrl:1
	v_sub_f32_e32 v3, v136, v2
	ds_read_b32 v136, v108 offset:576
	v_cndmask_b32_e64 v65, v65, v3, s[66:67]
	ds_write_b32 v123, v3 offset:2072
	s_waitcnt lgkmcnt(9)
	v_mul_f32_e32 v2, v138, v64
	v_fmac_f32_e32 v2, v140, v66
	v_fmac_f32_e32 v2, v141, v67
	v_fmac_f32_e32 v2, v139, v65
	ds_read2_b32 v[138:139], v73 offset0:160 offset1:164
	ds_read2_b32 v[140:141], v73 offset0:168 offset1:172
	v_add_f32_dpp v2, v2, v2 quad_perm:[1,0,3,2] row_mask:0xf bank_mask:0xf bound_ctrl:1
	s_nop 1
	v_add_f32_dpp v2, v2, v2 quad_perm:[2,3,0,1] row_mask:0xf bank_mask:0xf bound_ctrl:1
	v_sub_f32_e32 v129, v137, v2
	ds_read_b32 v137, v108 offset:640
	v_cndmask_b32_e64 v65, v65, v129, s[68:69]
	ds_write_b32 v123, v129 offset:2076
	s_waitcnt lgkmcnt(9)
	v_mul_f32_e32 v2, v68, v64
	v_fmac_f32_e32 v2, v70, v66
	v_fmac_f32_e32 v2, v71, v67
	v_fmac_f32_e32 v2, v69, v65
	ds_read2_b32 v[68:69], v73 offset0:176 offset1:180
	ds_read2_b32 v[70:71], v73 offset0:184 offset1:188
	v_add_f32_dpp v2, v2, v2 quad_perm:[1,0,3,2] row_mask:0xf bank_mask:0xf bound_ctrl:1
	s_nop 1
	v_add_f32_dpp v2, v2, v2 quad_perm:[2,3,0,1] row_mask:0xf bank_mask:0xf bound_ctrl:1
	v_sub_f32_e32 v3, v142, v2
	ds_read_b32 v142, v108 offset:704
	v_cndmask_b32_e64 v66, v66, v3, s[62:63]
	ds_write_b32 v123, v3 offset:2080
	s_waitcnt lgkmcnt(9)
	v_mul_f32_e32 v2, v132, v64
	v_fmac_f32_e32 v2, v133, v65
	v_fmac_f32_e32 v2, v135, v67
	v_fmac_f32_e32 v2, v134, v66
	ds_read2_b32 v[132:133], v73 offset0:192 offset1:196
	ds_read2_b32 v[134:135], v73 offset0:200 offset1:204
	v_add_f32_dpp v2, v2, v2 quad_perm:[1,0,3,2] row_mask:0xf bank_mask:0xf bound_ctrl:1
	s_nop 1
	v_add_f32_dpp v2, v2, v2 quad_perm:[2,3,0,1] row_mask:0xf bank_mask:0xf bound_ctrl:1
	v_sub_f32_e32 v129, v136, v2
	ds_read_b32 v136, v108 offset:768
	v_cndmask_b32_e64 v66, v66, v129, s[64:65]
	ds_write_b32 v123, v129 offset:2084
	s_waitcnt lgkmcnt(9)
	v_mul_f32_e32 v2, v138, v64
	v_fmac_f32_e32 v2, v139, v65
	v_fmac_f32_e32 v2, v141, v67
	v_fmac_f32_e32 v2, v140, v66
	ds_read2_b32 v[138:139], v73 offset0:208 offset1:212
	ds_read2_b32 v[140:141], v73 offset0:216 offset1:220
	v_add_f32_dpp v2, v2, v2 quad_perm:[1,0,3,2] row_mask:0xf bank_mask:0xf bound_ctrl:1
	s_nop 1
	v_add_f32_dpp v2, v2, v2 quad_perm:[2,3,0,1] row_mask:0xf bank_mask:0xf bound_ctrl:1
	v_sub_f32_e32 v3, v137, v2
	ds_read_b32 v137, v108 offset:832
	v_cndmask_b32_e64 v66, v66, v3, s[66:67]
	ds_write_b32 v123, v3 offset:2088
	s_waitcnt lgkmcnt(9)
; #define WAVE_SYNC() do { __builtin_amdgcn_fence(__ATOMIC_SEQ_CST, "wavefront"); __builtin_amdgcn_wave_barrier(); } while (0)
; __device__ __forceinline__ void gdn_block4(const Params& p, int l, int b, int h, int dir, char* smem, bool ctx_out) {
;     ...
;           float part = 0.f;
; #pragma unroll
;           for (int j = 0; j < (t + 3) / 4; ++j) part += a1[j] * dreg[j];
;           part = reduce4(part);
;           const float dt = bt * vv - bt * ec * ksv - part;
;           dreg[t >> 2] = (sq == (t & 3)) ? dt : dreg[t >> 2];
;           float po = 0.f;
; #pragma unroll
;           for (int j = 0; j <= (t >> 2); ++j) po += a2[j] * dreg[j];
;           po = reduce4(po);
;           Lo[(tb + t) * 64 + wid * 16 + vq] = ec * qsv + po;
;           DlT[vq * 16 + t] = dt;
;         }
;         WAVE_SYNC();
;         {
;           const float Dd = Ecs[15];
;           bf16x8 df = {0, 0, 0, 0, 0, 0, 0, 0};
;           float4 e0 = make_float4(0.f, 0.f, 0.f, 0.f), e1 = e0;
;           if (fq < 2) {
;             const float4 x0 = *reinterpret_cast<const float4*>(DlT + fr * 16 + fq * 8), x1 = *reinterpret_cast<const float4*>(DlT + fr * 16 + fq * 8 + 4);
;             const uint4 ux = make_uint4(pack2(x0.x, x0.y), pack2(x0.z, x0.w), pack2(x1.x, x1.y), pack2(x1.z, x1.w));
;             df = __builtin_bit_cast(bf16x8, ux);
;             e0 = *reinterpret_cast<const float4*>(E15 + fq * 8); e1 = *reinterpret_cast<const float4*>(E15 + fq * 8 + 4);
;           }
	v_mul_f32_e32 v2, v68, v64
	v_fmac_f32_e32 v2, v69, v65
	v_fmac_f32_e32 v2, v71, v67
	v_fmac_f32_e32 v2, v70, v66
	ds_read2_b32 v[68:69], v73 offset0:224 offset1:228
	ds_read2_b32 v[70:71], v73 offset0:232 offset1:236
	v_add_f32_dpp v2, v2, v2 quad_perm:[1,0,3,2] row_mask:0xf bank_mask:0xf bound_ctrl:1
	s_nop 1
	v_add_f32_dpp v2, v2, v2 quad_perm:[2,3,0,1] row_mask:0xf bank_mask:0xf bound_ctrl:1
	v_sub_f32_e32 v129, v142, v2
	ds_read_b32 v142, v108 offset:896
	v_cndmask_b32_e64 v66, v66, v129, s[68:69]
	ds_write_b32 v123, v129 offset:2092
	s_waitcnt lgkmcnt(9)
	v_mul_f32_e32 v2, v132, v64
	v_fmac_f32_e32 v2, v133, v65
	v_fmac_f32_e32 v2, v135, v67
	v_fmac_f32_e32 v2, v134, v66
	ds_read2_b32 v[132:133], v73 offset0:240 offset1:244
	ds_read2_b32 v[134:135], v73 offset0:248 offset1:252
	v_add_f32_dpp v2, v2, v2 quad_perm:[1,0,3,2] row_mask:0xf bank_mask:0xf bound_ctrl:1
	s_nop 1
	v_add_f32_dpp v2, v2, v2 quad_perm:[2,3,0,1] row_mask:0xf bank_mask:0xf bound_ctrl:1
	v_sub_f32_e32 v3, v136, v2
	ds_read_b32 v136, v108 offset:960
	v_cndmask_b32_e64 v67, v67, v3, s[62:63]
	ds_write_b32 v123, v3 offset:2096
	s_waitcnt lgkmcnt(9)
	v_mul_f32_e32 v2, v138, v64
	v_fmac_f32_e32 v2, v139, v65
	v_fmac_f32_e32 v2, v140, v66
	v_fmac_f32_e32 v2, v141, v67
	s_nop 1
	v_add_f32_dpp v2, v2, v2 quad_perm:[1,0,3,2] row_mask:0xf bank_mask:0xf bound_ctrl:1
	s_nop 1
	v_add_f32_dpp v2, v2, v2 quad_perm:[2,3,0,1] row_mask:0xf bank_mask:0xf bound_ctrl:1
	v_sub_f32_e32 v129, v137, v2
	v_cndmask_b32_e64 v67, v67, v129, s[64:65]
	ds_write_b32 v123, v129 offset:2100
	s_waitcnt lgkmcnt(6)
	v_mul_f32_e32 v2, v68, v64
	v_fmac_f32_e32 v2, v69, v65
	v_fmac_f32_e32 v2, v70, v66
	v_fmac_f32_e32 v2, v71, v67
	s_nop 1
	v_add_f32_dpp v2, v2, v2 quad_perm:[1,0,3,2] row_mask:0xf bank_mask:0xf bound_ctrl:1
	s_nop 1
	v_add_f32_dpp v2, v2, v2 quad_perm:[2,3,0,1] row_mask:0xf bank_mask:0xf bound_ctrl:1
	v_sub_f32_e32 v3, v142, v2
	v_cndmask_b32_e64 v67, v67, v3, s[66:67]
	ds_write_b32 v123, v3 offset:2104
	s_waitcnt lgkmcnt(3)
	v_mul_f32_e32 v2, v132, v64
	v_fmac_f32_e32 v2, v133, v65
	v_fmac_f32_e32 v2, v134, v66
	v_fmac_f32_e32 v2, v135, v67
	s_nop 1
	v_add_f32_dpp v2, v2, v2 quad_perm:[1,0,3,2] row_mask:0xf bank_mask:0xf bound_ctrl:1
	s_nop 1
	v_add_f32_dpp v2, v2, v2 quad_perm:[2,3,0,1] row_mask:0xf bank_mask:0xf bound_ctrl:1
	v_sub_f32_e32 v129, v136, v2
	v_cndmask_b32_e64 v67, v67, v129, s[68:69]
	ds_write_b32 v123, v129 offset:2108
	v_lshlrev_b32_e32 v2, 2, v98
	v_sub_u32_e32 v3, v111, v2
	ds_read_b128 v[56:59], v3 offset:2048
	v_lshl_add_u32 v2, v97, 6, v2
	v_add_u32_e32 v2, vcc_hi, v2
	ds_read_b128 v[132:135], v2 offset:1024
	s_waitcnt lgkmcnt(0)
	v_mfma_f32_16x16x4_f32 v[60:63], v132, v56, v[60:63]
	v_mfma_f32_16x16x4_f32 v[60:63], v133, v57, v[60:63]
	v_mfma_f32_16x16x4_f32 v[60:63], v134, v58, v[60:63]
	v_mfma_f32_16x16x4_f32 v[60:63], v135, v59, v[60:63]
	s_nop 9
	ds_write_b32 v131, v60
	ds_write_b32 v131, v61 offset:256
	ds_write_b32 v131, v62 offset:512
	ds_write_b32 v131, v63 offset:768
	v_mov_b32_e32 v58, 0
	v_mov_b32_e32 v59, 0
	v_mov_b32_e32 v60, 0
	v_mov_b32_e32 v61, 0
	v_mov_b32_e32 v62, 0
	v_mov_b32_e32 v63, 0
	v_mov_b32_e32 v68, 0
	ds_read_b32 v2, v72 offset:2108
	v_mov_b32_e32 v56, 0
	v_mov_b32_e32 v57, 0
	v_mov_b32_e32 v66, 0
	v_mov_b32_e32 v67, 0
	v_mov_b32_e32 v64, 0
	v_mov_b32_e32 v65, 0
	s_and_saveexec_b64 s[90:91], s[8:9]
	s_cbranch_execz .LBB0_1244
	ds_read_b128 v[56:59], v111 offset:2048
	ds_read_b128 v[62:65], v111 offset:2064
	v_lshl_add_u32 v3, v100, 2, vcc_hi
	s_waitcnt lgkmcnt(1)
	v_cvt_pk_bf16_f32 v60, v56, v57
	v_cvt_pk_bf16_f32 v61, v58, v59
	s_waitcnt lgkmcnt(0)
	v_cvt_pk_bf16_f32 v62, v62, v63
	v_cvt_pk_bf16_f32 v63, v64, v65
	ds_read_b128 v[64:67], v3 offset:2112
	ds_read_b128 v[56:59], v3 offset:2128
